# diff attention PV: V-fragment refill reads issued two per MFMA instead of a burst of eight
# baseline (speedup 1.0000x reference)
; DI f32x16 mfma32(bf16x8 a, bf16x8 b, f32x16 c) { return __builtin_amdgcn_mfma_f32_32x32x16_bf16(a, b, c, 0, 0, 0); }
; DI void diff_item(const Params& p, int l, int qt, int bh, char* smem) {
;     ...
; #pragma unroll
;     for (int k2 = 0; k2 < 2; ++k2)
; #pragma unroll
;       for (int j = 0; j < 16; ++j) sa[k2][j] = __builtin_amdgcn_exp2f(sa[k2][j]);
; #pragma unroll
;     for (int k2 = 0; k2 < 2; ++k2)
; #pragma unroll
;       for (int s2 = 0; s2 < 2; ++s2) {
;         const bf16x8 pp = pack8(sa[k2], s2);
;         bf16x8 vf[4];
;         trfrag4<320>(Vs, 32 * k2 + 16 * s2, ln, vf);
; #pragma unroll
;         for (int mt = 0; mt < 4; ++mt) O[mt] = mfma32(vf[mt], pp, O[mt]);
;         Lacc = mfma32(onesf, pp, Lacc);
;       }
.LBB0_577:
	v_add3_u32 v182, v168, v169, s98
	s_waitcnt lgkmcnt(1)
	ds_read_b64_tr_b16 v[226:227], v182 offset:22528
	ds_read_b64_tr_b16 v[228:229], v182 offset:25088
	ds_read_b64_tr_b16 v[230:231], v182 offset:22592
	ds_read_b64_tr_b16 v[232:233], v182 offset:25152
	ds_read_b64_tr_b16 v[234:235], v182 offset:22656
	ds_read_b64_tr_b16 v[236:237], v182 offset:25216
	ds_read_b64_tr_b16 v[238:239], v182 offset:22720
	ds_read_b64_tr_b16 v[240:241], v182 offset:25280
	v_exp_f32_e32 v84, v84
	v_exp_f32_e32 v85, v85
	v_exp_f32_e32 v86, v86
	v_exp_f32_e32 v87, v87
	v_exp_f32_e32 v88, v88
	v_exp_f32_e32 v89, v89
	v_exp_f32_e32 v90, v90
	v_exp_f32_e32 v91, v91
	v_exp_f32_e32 v92, v92
	v_exp_f32_e32 v93, v93
	v_cvt_pk_bf16_f32 v84, v84, v85
	v_cvt_pk_bf16_f32 v85, v86, v87
	v_cvt_pk_bf16_f32 v86, v88, v89
	v_cvt_pk_bf16_f32 v87, v90, v91
	s_nop 0
	s_waitcnt lgkmcnt(8)
	v_mfma_f32_32x32x16_bf16 v[52:67], v[210:213], v[84:87], v[52:67]
	ds_read_b64_tr_b16 v[210:211], v182 offset:27648
	ds_read_b64_tr_b16 v[212:213], v182 offset:30208
	v_exp_f32_e32 v94, v94
	v_exp_f32_e32 v95, v95
	v_mfma_f32_32x32x16_bf16 v[36:51], v[214:217], v[84:87], v[36:51]
	ds_read_b64_tr_b16 v[214:215], v182 offset:27712
	ds_read_b64_tr_b16 v[216:217], v182 offset:30272
	v_exp_f32_e32 v96, v96
	v_exp_f32_e32 v97, v97
	v_mfma_f32_32x32x16_bf16 v[20:35], v[218:221], v[84:87], v[20:35]
	ds_read_b64_tr_b16 v[218:219], v182 offset:27776
	ds_read_b64_tr_b16 v[220:221], v182 offset:30336
	v_exp_f32_e32 v98, v98
	v_exp_f32_e32 v99, v99
	v_mfma_f32_32x32x16_bf16 v[4:19], v[222:225], v[84:87], v[4:19]
	ds_read_b64_tr_b16 v[222:223], v182 offset:27840
	ds_read_b64_tr_b16 v[224:225], v182 offset:30400
	v_exp_f32_e32 v100, v100
	v_exp_f32_e32 v101, v101
	v_mfma_f32_32x32x16_bf16 v[68:83], v[116:119], v[84:87], v[68:83]
	v_cvt_pk_bf16_f32 v92, v92, v93
	v_cvt_pk_bf16_f32 v93, v94, v95
	v_cvt_pk_bf16_f32 v94, v96, v97
	v_cvt_pk_bf16_f32 v95, v98, v99
	s_nop 0
	s_waitcnt lgkmcnt(8)
	v_mfma_f32_32x32x16_bf16 v[52:67], v[226:229], v[92:95], v[52:67]
	ds_read_b64_tr_b16 v[226:227], v182 offset:32768
	ds_read_b64_tr_b16 v[228:229], v182 offset:35328
	v_exp_f32_e32 v102, v102
	v_exp_f32_e32 v103, v103
	v_mfma_f32_32x32x16_bf16 v[36:51], v[230:233], v[92:95], v[36:51]
	ds_read_b64_tr_b16 v[230:231], v182 offset:32832
	ds_read_b64_tr_b16 v[232:233], v182 offset:35392
	v_exp_f32_e32 v104, v104
	v_exp_f32_e32 v105, v105
	v_mfma_f32_32x32x16_bf16 v[20:35], v[234:237], v[92:95], v[20:35]
	ds_read_b64_tr_b16 v[234:235], v182 offset:32896
	ds_read_b64_tr_b16 v[236:237], v182 offset:35456
	v_exp_f32_e32 v106, v106
	v_exp_f32_e32 v107, v107
	v_mfma_f32_32x32x16_bf16 v[4:19], v[238:241], v[92:95], v[4:19]
	ds_read_b64_tr_b16 v[238:239], v182 offset:32960
	ds_read_b64_tr_b16 v[240:241], v182 offset:35520
	v_exp_f32_e32 v108, v108
	v_exp_f32_e32 v109, v109
	v_mfma_f32_32x32x16_bf16 v[68:83], v[116:119], v[92:95], v[68:83]
	v_cvt_pk_bf16_f32 v100, v100, v101
	v_cvt_pk_bf16_f32 v101, v102, v103
	v_cvt_pk_bf16_f32 v102, v104, v105
	v_cvt_pk_bf16_f32 v103, v106, v107
	s_nop 0
	s_waitcnt lgkmcnt(8)
	v_mfma_f32_32x32x16_bf16 v[52:67], v[210:213], v[100:103], v[52:67]
	v_exp_f32_e32 v110, v110
	v_exp_f32_e32 v111, v111
	v_mfma_f32_32x32x16_bf16 v[36:51], v[214:217], v[100:103], v[36:51]
	v_exp_f32_e32 v112, v112
	v_exp_f32_e32 v113, v113
	v_mfma_f32_32x32x16_bf16 v[20:35], v[218:221], v[100:103], v[20:35]
	v_exp_f32_e32 v114, v114
	v_exp_f32_e32 v115, v115
	v_mfma_f32_32x32x16_bf16 v[4:19], v[222:225], v[100:103], v[4:19]
	v_mfma_f32_32x32x16_bf16 v[68:83], v[116:119], v[100:103], v[68:83]
	v_cvt_pk_bf16_f32 v108, v108, v109
	v_cvt_pk_bf16_f32 v109, v110, v111
	v_cvt_pk_bf16_f32 v110, v112, v113
	v_cvt_pk_bf16_f32 v111, v114, v115
	s_nop 0
	s_waitcnt lgkmcnt(0)
	v_mfma_f32_32x32x16_bf16 v[52:67], v[226:229], v[108:111], v[52:67]
	v_mfma_f32_32x32x16_bf16 v[36:51], v[230:233], v[108:111], v[36:51]
	v_mfma_f32_32x32x16_bf16 v[20:35], v[234:237], v[108:111], v[20:35]
	v_mfma_f32_32x32x16_bf16 v[4:19], v[238:241], v[108:111], v[4:19]
	v_mfma_f32_32x32x16_bf16 v[68:83], v[116:119], v[108:111], v[68:83]
